# grid barrier: the workgroup arriving as 3/4 of its XCD issues an early buffer_wbl2 so most dirty lines are flushed before the last arrival
# speedup vs baseline: 1.0074x; 1.0074x over previous
; __device__ __forceinline__ unsigned xb_ld(unsigned* p)              { return __hip_atomic_load(p, __ATOMIC_RELAXED, __HIP_MEMORY_SCOPE_AGENT); }
; __device__ __forceinline__ unsigned xb_add(unsigned* p, unsigned v) { return __hip_atomic_fetch_add(p, v, __ATOMIC_RELAXED, __HIP_MEMORY_SCOPE_AGENT); }
; #define XB_SPIN(cond, bar) do { unsigned _sp = 0; while (cond) { __builtin_amdgcn_s_sleep(1); \
;     if ((++_sp & 255u) == 0u) { if (xb_ld(&(bar)[XB_TMO])) break; if (_sp > XB_SPIN_CAP) { atomicAdd(&(bar)[XB_TMO], 1u); break; } } } } while (0)
; __device__ __forceinline__ void xcd_barrier(const XcdBarrier& b) {
;     ...
;         const unsigned old = xb_add(&bar[XB_XSUB(b.x)], 1u);
;         const unsigned gen = old / nloc;
;         if (old + 1u == (gen + 1u) * nloc) {
;             __builtin_amdgcn_fence(__ATOMIC_RELEASE, "agent");
;             asm volatile("s_waitcnt vmcnt(0)" ::: "memory");
;             const unsigned og = xb_add(&bar[XB_TOP], 1u);
;             const unsigned tg = og / nx;
;             if (og + 1u == (tg + 1u) * nx) xb_add(&bar[XB_TOPGEN], 1u);
;             else XB_SPIN(xb_ld(&bar[XB_TOPGEN]) == tg, bar);
;             __builtin_amdgcn_fence(__ATOMIC_ACQUIRE, "agent");
;             xb_add(&bar[XB_XGEN(b.x)], 1u);
;             asm volatile("s_waitcnt vmcnt(0)" ::: "memory");
;         } else {
;             XB_SPIN(xb_ld(&bar[XB_XGEN(b.x)]) == gen, bar);
.LBB0_590:
	v_readlane_b32 s2, v254, 0
	v_readlane_b32 s3, v254, 1
	v_mov_b32_e32 v1, 1
	v_sub_u32_e32 v4, 0, v2
	s_nop 2
	global_atomic_add v3, v96, v1, s[2:3] sc0
	v_cvt_f32_u32_e32 v1, v2
	v_rcp_iflag_f32_e32 v1, v1
	s_nop 0
	v_mul_f32_e32 v1, 0x4f7ffffe, v1
	v_cvt_u32_f32_e32 v1, v1
	v_mul_lo_u32 v4, v4, v1
	v_mul_hi_u32 v4, v1, v4
	v_add_u32_e32 v1, v1, v4
	s_waitcnt vmcnt(0)
	v_mul_hi_u32 v1, v3, v1
	v_mul_lo_u32 v4, v1, v2
	v_sub_u32_e32 v4, v3, v4
	v_add_u32_e32 v5, 1, v1
	v_cmp_ge_u32_e32 vcc, v4, v2
	v_add_u32_e32 v3, 1, v3
	s_nop 0
	v_cndmask_b32_e32 v1, v1, v5, vcc
	v_sub_u32_e32 v5, v4, v2
	v_cndmask_b32_e32 v4, v4, v5, vcc
	v_add_u32_e32 v5, 1, v1
	v_cmp_ge_u32_e32 vcc, v4, v2
	s_nop 1
	v_cndmask_b32_e32 v1, v1, v5, vcc
	v_mul_lo_u32 v4, v2, v1
	v_add_u32_e32 v2, v4, v2
	v_cmp_ne_u32_e32 vcc, v3, v2
	v_sub_u32_e32 v5, v2, v4
	v_lshrrev_b32_e32 v5, 2, v5
	v_sub_u32_e32 v5, v2, v5
	v_cmp_eq_u32_e64 s[10:11], v3, v5
	v_add_u32_e32 v4, 1, v1
	s_waitcnt lgkmcnt(0)
	v_mul_lo_u32 v4, v4, v0
	v_readlane_b32 s2, v254, 4
	v_readlane_b32 s3, v254, 5
	s_nop 4
	s_cbranch_vccnz .Lxb_notlast
	buffer_wbl2 sc1
	s_waitcnt vmcnt(0)
	v_mov_b32_e32 v1, 1
	global_atomic_add v96, v1, s[2:3]
	s_branch .Lxb_poll
